# conv-GLU fix-up pass: second conv_w load issued with the first instead of after a vmcnt(0) round trip
# baseline (speedup 1.0000x reference)
; __device__ __forceinline__ unsigned f2bf(float f) { unsigned u = __builtin_bit_cast(unsigned, f); return (u + 0x7fffu + ((u >> 16) & 1u)) >> 16; }
; __device__ __forceinline__ void convfix_pass(const Params& p, int G) {
;     ...
;         const int c = w & 127, i = (w >> 7) & 1, tile = w >> 8, pn = tile % 86, pm = tile / 86, ch = pn * 128 + c, t = pm * 256 + i;
;         const float cpart = fixb[((size_t)tile * 2 + i) * 256 + c], up = fixb[((size_t)tile * 2 + i) * 256 + 128 + c];
;         float h0 = 0.f, h1 = 0.f;
;         if ((pm & 31) != 0) { const size_t hb = ((size_t)((pm - 1) * 86 + pn) * 2) * 128 + c; h0 = halo[hb]; h1 = halo[hb + 128]; }
;         const float w0 = p.conv_w[ch], w1 = p.conv_w[DFF + ch];
;         const float cv = cpart + (i == 0 ? w0 * h0 + w1 * h1 : w0 * h1);
;         act[(size_t)t * DFF + ch] = (bf16)f2bf(cv / (1.f + __expf(-cv)) * up);
.LBB0_867:
	s_or_b64 exec, exec, s[8:9]
	v_lshl_or_b32 v12, v12, 7, v2
	v_ashrrev_i32_e32 v13, 31, v12
	v_lshl_add_u64 v[18:19], v[12:13], 2, s[60:61]
	global_load_dword v16, v[18:19], off
	v_add_co_u32_e32 v22, vcc, 0xa000, v18
	s_nop 1
	v_addc_co_u32_e32 v23, vcc, 0, v19, vcc
	global_load_dword v24, v[22:23], off offset:3072
	v_cmp_ne_u32_e32 vcc, 0, v3
	s_and_saveexec_b64 s[8:9], vcc
	s_xor_b64 s[8:9], exec, s[8:9]
	s_cbranch_execz .LBB0_869
	s_waitcnt vmcnt(0)
	v_mul_f32_e32 v17, v15, v16
.LBB0_869:
	s_andn2_saveexec_b64 s[8:9], s[8:9]
	s_cbranch_execz .LBB0_864
	s_waitcnt vmcnt(0)
	v_mov_b32_e32 v17, v24
	v_pk_mul_f32 v[14:15], v[14:15], v[16:17]
	s_nop 0
	v_add_f32_e32 v17, v14, v15
	s_branch .LBB0_864
